# sample-group HGRN recurrence units: RMSNorm tail's two loads issued with the unit's load batch; the tail no longer drains the 32 state stores before it can finish
# speedup vs baseline: 1.0192x; 1.0006x over previous
; #define LAS __attribute__((address_space(3)))
; template <class Tp> DEV Tp* wsp(const Frame& F, size_t off) { return (Tp*)(F.ws + off); }
; DEV void hgrn_sample_unit(Frame& F, int b, int h) {
;     ...
;     const int tid = F.tid, v = tid & 127, kq = tid >> 7;
;     const float* TB = wsp<float>(F, WS_TBL);
;     const float* HF = wsp<float>(F, WS_HF); const bf16* HQ = wsp<bf16>(F, WS_HQ); const bf16* HI = wsp<bf16>(F, WS_HI);
;     { const int k = v, t = kq; const size_t g = (size_t)(T + b * 4 + t) * 512 + h * 128 + k; const float lbv = TB[TB_LB + h * 128 + k], oml = 1.0f - lbv;
;       const float z = HF[g]; Lf[t * 128 + k] = lbv + oml * __builtin_amdgcn_rcpf(1.0f + __expf(-z)); Lkk[t * 128 + k] = oml * __builtin_amdgcn_rcpf(1.0f + __expf(z)); Lqq[t * 128 + k] = bf2f(HQ[g]); }
;     float S[32];
;     const float* S0 = ((const float*)F.A.in[8]) + ((size_t)(b * 4 + h) * 128 + kq * 32) * 128 + v;
; #pragma unroll
;     for (int j = 0; j < 32; ++j) S[j] = S0[(size_t)j * 128];
;     __syncthreads();
;     for (int t = 0; t < 4; ++t) {
;         const float vt = bf2f(HI[(size_t)(T + b * 4 + t) * 512 + h * 128 + v]);
;     ...
;         const int t = F.wave, lane = F.lane; const f32x2 o = *(const LAS f32x2*)(Lot + t * 128 + 2 * lane);
;         const float ss = wave_sum(o.x * o.x + o.y * o.y); const float rr = 1.0f / sqrtf(ss * (1.f / 128.f) + EPS);
;         const size_t go = (size_t)(T + b * 4 + t) * 512 + h * 128 + 2 * lane; const unsigned gw_ = *(const unsigned*)(wsp<bf16>(F, WS_HG) + go);
.LBB0_1672:
	s_or_b64 exec, exec, s[4:5]
	s_waitcnt lgkmcnt(0)
	s_barrier
	ds_read_b32 v18, v40
	s_mov_b64 s[4:5], -1
	s_waitcnt lgkmcnt(0)
	s_barrier
	v_cmp_lt_i32_e32 vcc, s26, v18
	v_readfirstlane_b32 s22, v18
	s_cbranch_vccnz .LBB0_1667
	s_and_b32 s4, s22, -4
	s_addk_i32 s4, 0x4000
	v_add_u32_e32 v18, s4, v1
	v_ashrrev_i32_e32 v19, 31, v18
	s_lshl_b32 s5, s22, 7
	v_lshlrev_b64 v[18:19], 9, v[18:19]
	s_and_b32 s24, s5, 0x180
	v_or_b32_e32 v18, s24, v18
	v_or_b32_e32 v18, v18, v2
	v_lshl_add_u64 v[20:21], v[18:19], 2, s[14:15]
	global_load_dword v29, v[20:21], off
	v_or_b32_e32 v20, s24, v2
	v_lshlrev_b32_e32 v20, 2, v20
	global_load_dword v41, v20, s[12:13]
	v_lshl_add_u64 v[18:19], v[18:19], 1, s[16:17]
	global_load_ushort v42, v[18:19], off
	s_ashr_i32 s23, s22, 31
	s_lshl_b64 s[22:23], s[22:23], 14
	v_lshl_add_u64 v[18:19], s[22:23], 0, v[6:7]
	v_lshl_add_u64 v[22:23], v[18:19], 2, v[8:9]
	v_add_co_u32_e32 v24, vcc, s28, v22
	global_load_dword v136, v[22:23], off
	global_load_dword v137, v[22:23], off offset:512
	global_load_dword v140, v[22:23], off offset:1024
	global_load_dword v141, v[22:23], off offset:1536
	global_load_dword v142, v[22:23], off offset:2048
	global_load_dword v143, v[22:23], off offset:2560
	global_load_dword v144, v[22:23], off offset:3072
	global_load_dword v145, v[22:23], off offset:3584
	v_addc_co_u32_e32 v25, vcc, 0, v23, vcc
	v_add_co_u32_e32 v30, vcc, s29, v22
	s_lshl_b32 s18, s24, 1
	s_nop 0
	v_addc_co_u32_e32 v31, vcc, 0, v23, vcc
	v_add_co_u32_e32 v34, vcc, s30, v22
	s_ashr_i32 s5, s4, 31
	s_nop 0
	v_addc_co_u32_e32 v35, vcc, 0, v23, vcc
	global_load_dword v146, v[30:31], off
	global_load_dword v147, v[30:31], off offset:512
	global_load_dword v148, v[30:31], off offset:1024
	global_load_dword v149, v[30:31], off offset:1536
	global_load_dword v22, v[30:31], off offset:2048
	global_load_dword v23, v[30:31], off offset:2560
	global_load_dword v26, v[30:31], off offset:3072
	global_load_dword v27, v[30:31], off offset:3584
	global_load_dword v150, v[24:25], off offset:512
	global_load_dword v151, v[24:25], off offset:1024
	global_load_dword v152, v[24:25], off offset:1536
	global_load_dword v153, v[24:25], off offset:2048
	global_load_dword v154, v[24:25], off offset:2560
	global_load_dword v155, v[24:25], off offset:3072
	s_nop 0
	global_load_dword v25, v[24:25], off offset:3584
	s_nop 0
	global_load_dword v28, v[34:35], off
	v_lshl_add_u64 v[20:21], v[10:11], 0, s[18:19]
	s_lshl_b64 s[22:23], s[4:5], 10
	v_lshl_add_u64 v[36:37], v[20:21], 0, s[22:23]
	global_load_ushort v240, v[36:37], off
	global_load_ushort v241, v[36:37], off offset:1024
	global_load_ushort v242, v[36:37], off offset:2048
	global_load_ushort v243, v[36:37], off offset:3072
	s_min_u32 s32, s79, 3
	s_add_i32 s32, s4, s32
	s_ashr_i32 s33, s32, 31
	s_lshl_b64 s[32:33], s[32:33], 9
	v_mov_b32_e32 v228, s24
	v_or3_b32 v229, s33, 0, 0
	v_or3_b32 v228, s32, v228, v14
	v_lshlrev_b64 v[228:229], 1, v[228:229]
	v_lshl_add_u64 v[228:229], s[6:7], 0, v[228:229]
	global_load_dwordx2 v[232:233], v[16:17], off
	global_load_dword v234, v[228:229], off
	s_waitcnt vmcnt(32)
	v_mul_f32_e32 v24, 0xbfb8aa3b, v29
	v_mul_f32_e32 v29, 0x3fb8aa3b, v29
	v_exp_f32_e32 v24, v24
	v_exp_f32_e32 v43, v29
	global_load_dword v156, v[30:31], off offset:-4096
	global_load_dword v29, v[34:35], off offset:512
	s_nop 0
	global_load_dword v30, v[34:35], off offset:1024
	global_load_dword v31, v[34:35], off offset:1536
	global_load_dword v32, v[34:35], off offset:2048
	global_load_dword v33, v[34:35], off offset:2560
	global_load_dword v134, v[34:35], off offset:3072
	global_load_dword v135, v[34:35], off offset:3584
	s_waitcnt vmcnt(39)
	v_sub_f32_e32 v34, 1.0, v41
	v_add_f32_e32 v24, 1.0, v24
	v_add_f32_e32 v35, 1.0, v43
	v_rcp_f32_e32 v24, v24
	v_rcp_f32_e32 v35, v35
	s_waitcnt vmcnt(38)
	v_lshlrev_b32_e32 v42, 16, v42
	ds_write_b32 v160, v42 offset:4096
	v_fmac_f32_e32 v41, v34, v24
	v_mul_f32_e32 v24, v34, v35
	ds_write2st64_b32 v160, v41, v24 offset1:8
	s_waitcnt lgkmcnt(0)
	s_barrier
; DEV void hgrn_sample_unit(Frame& F, int b, int h) {
;     ...
;     for (int t = 0; t < 4; ++t) {
;         const float vt = bf2f(HI[(size_t)(T + b * 4 + t) * 512 + h * 128 + v]);
;         float o = 0.f;
; #pragma unroll
;         for (int j = 0; j < 32; ++j) { const int k = kq * 32 + j; S[j] = Lf[t * 128 + k] * S[j] + Lkk[t * 128 + k] * vt; o += Lqq[t * 128 + k] * S[j]; }
;         Lo[kq * 128 + v] = o;
;         __syncthreads();
;         if (kq == 0) Lot[t * 128 + v] = (Lo[v] + Lo[128 + v]) + (Lo[256 + v] + Lo[384 + v]);
;         __syncthreads();
	ds_read_b128 v[58:61], v4
	ds_read_b128 v[62:65], v4 offset:16
	ds_read_b128 v[66:69], v4 offset:32
	ds_read_b128 v[70:73], v4 offset:48
	ds_read_b128 v[34:37], v4 offset:2048
	ds_read_b128 v[42:45], v4 offset:2064
	ds_read_b128 v[74:77], v4 offset:4096
	ds_read_b128 v[78:81], v4 offset:4112
	ds_read_b128 v[46:49], v4 offset:2080
	ds_read_b128 v[50:53], v4 offset:2096
	ds_read_b128 v[82:85], v4 offset:4128
	ds_read_b128 v[86:89], v4 offset:4144
	ds_read_b128 v[90:93], v4 offset:4160
	ds_read_b128 v[94:97], v4 offset:4176
	ds_read_b128 v[98:101], v4 offset:64
	ds_read_b128 v[102:105], v4 offset:80
	ds_read_b128 v[54:57], v4 offset:2112
	ds_read_b128 v[106:109], v4 offset:2128
	ds_read_b128 v[110:113], v4 offset:4192
	ds_read_b128 v[114:117], v4 offset:4208
	ds_read_b128 v[118:121], v4 offset:96
	ds_read_b128 v[122:125], v4 offset:112
	ds_read_b128 v[126:129], v4 offset:2144
	ds_read_b128 v[130:133], v4 offset:2160
	s_waitcnt vmcnt(0)
	v_lshlrev_b32_e32 v24, 16, v240
	s_waitcnt lgkmcnt(14)
	v_mul_f32_e32 v34, v34, v24
	v_mul_f32_e32 v35, v35, v24
	v_fmac_f32_e32 v34, v136, v58
	v_mul_f32_e32 v36, v36, v24
	v_mul_f32_e32 v41, v42, v24
	v_mul_f32_e32 v42, v43, v24
	v_mul_f32_e32 v43, v44, v24
	v_mul_f32_e32 v44, v45, v24
	v_mul_f32_e32 v45, v46, v24
	v_mul_f32_e32 v46, v47, v24
	v_mul_f32_e32 v47, v48, v24
	v_mul_f32_e32 v48, v49, v24
	v_mul_f32_e32 v49, v50, v24
	v_mul_f32_e32 v50, v51, v24
	v_mul_f32_e32 v51, v52, v24
	v_mul_f32_e32 v52, v53, v24
	s_waitcnt lgkmcnt(7)
	v_mul_f32_e32 v53, v54, v24
	v_mul_f32_e32 v54, v55, v24
	v_mul_f32_e32 v55, v56, v24
	v_mul_f32_e32 v56, v57, v24
	v_fmac_f32_e32 v35, v137, v59
	v_fma_f32 v57, v74, v34, 0
	v_mul_f32_e32 v37, v37, v24
	v_fmac_f32_e32 v36, v140, v60
	v_fmac_f32_e32 v57, v75, v35
	v_fmac_f32_e32 v37, v141, v61
	v_fmac_f32_e32 v57, v76, v36
	v_fmac_f32_e32 v41, v142, v62
	v_fmac_f32_e32 v57, v77, v37
	v_fmac_f32_e32 v42, v143, v63
	v_fmac_f32_e32 v57, v78, v41
	v_fmac_f32_e32 v43, v144, v64
	v_fmac_f32_e32 v57, v79, v42
	v_fmac_f32_e32 v44, v145, v65
	v_fmac_f32_e32 v57, v80, v43
	v_fmac_f32_e32 v45, v156, v66
	v_fmac_f32_e32 v57, v81, v44
	v_fmac_f32_e32 v46, v150, v67
	v_fmac_f32_e32 v57, v82, v45
	v_fmac_f32_e32 v47, v151, v68
	v_fmac_f32_e32 v57, v83, v46
	v_fmac_f32_e32 v48, v152, v69
	v_fmac_f32_e32 v57, v84, v47
	v_fmac_f32_e32 v49, v153, v70
	v_fmac_f32_e32 v57, v85, v48
	v_fmac_f32_e32 v50, v154, v71
	v_fmac_f32_e32 v57, v86, v49
	v_fmac_f32_e32 v51, v155, v72
	v_fmac_f32_e32 v57, v87, v50
	v_fmac_f32_e32 v52, v25, v73
	v_fmac_f32_e32 v57, v88, v51
	v_fmac_f32_e32 v53, v146, v98
	v_fmac_f32_e32 v57, v89, v52
	v_fmac_f32_e32 v54, v147, v99
	v_fmac_f32_e32 v57, v90, v53
	v_fmac_f32_e32 v55, v148, v100
	v_fmac_f32_e32 v57, v91, v54
	s_waitcnt lgkmcnt(6)
	v_pk_mul_f32 v[106:107], v[106:107], v[24:25] op_sel_hi:[1,0]
	v_fmac_f32_e32 v56, v149, v101
	v_fmac_f32_e32 v57, v92, v55
	v_pk_mul_f32 v[108:109], v[108:109], v[24:25] op_sel_hi:[1,0]
	s_waitcnt lgkmcnt(1)
	v_pk_mul_f32 v[126:127], v[126:127], v[24:25] op_sel_hi:[1,0]
	v_pk_mul_f32 v[128:129], v[128:129], v[24:25] op_sel_hi:[1,0]
	s_waitcnt lgkmcnt(0)
	v_pk_mul_f32 v[130:131], v[130:131], v[24:25] op_sel_hi:[1,0]
	v_pk_mul_f32 v[132:133], v[132:133], v[24:25] op_sel_hi:[1,0]
	v_pk_fma_f32 v[24:25], v[22:23], v[102:103], v[106:107]
	v_fmac_f32_e32 v57, v93, v56
	v_fmac_f32_e32 v57, v94, v24
	v_pk_fma_f32 v[26:27], v[26:27], v[104:105], v[108:109]
	v_fmac_f32_e32 v57, v95, v25
	v_fmac_f32_e32 v57, v96, v26
	v_pk_fma_f32 v[28:29], v[28:29], v[118:119], v[126:127]
	v_fmac_f32_e32 v57, v97, v27
	v_fmac_f32_e32 v57, v110, v28
	v_pk_fma_f32 v[30:31], v[30:31], v[120:121], v[128:129]
	v_fmac_f32_e32 v57, v111, v29
	v_fmac_f32_e32 v57, v112, v30
	v_pk_fma_f32 v[32:33], v[32:33], v[122:123], v[130:131]
	v_fmac_f32_e32 v57, v113, v31
	v_fmac_f32_e32 v57, v114, v32
	v_pk_fma_f32 v[22:23], v[134:135], v[124:125], v[132:133]
	v_fmac_f32_e32 v57, v115, v33
	v_fmac_f32_e32 v57, v116, v22
	v_fmac_f32_e32 v57, v117, v23
	ds_write_b32 v160, v57 offset:6144
	s_waitcnt lgkmcnt(0)
	s_barrier
	s_and_saveexec_b64 s[22:23], s[2:3]
	s_cbranch_execz .LBB0_1675
	ds_read2st64_b32 v[58:59], v160 offset0:26 offset1:28
	ds_read_b32 v60, v3 offset:6144
	ds_read_b32 v61, v160 offset:7680
	s_waitcnt lgkmcnt(0)
	v_pk_add_f32 v[58:59], v[58:59], v[60:61]
	s_nop 0
	v_add_f32_e32 v57, v58, v59
	ds_write_b32 v160, v57 offset:8192

; #define LAS __attribute__((address_space(3)))
; DEV unsigned pk2(float lo, float hi) { return pg8::cvt_pk_bf16(lo, hi); }
; template <class Tp> DEV Tp* wsp(const Frame& F, size_t off) { return (Tp*)(F.ws + off); }
; DEV void hgrn_sample_unit(Frame& F, int b, int h) {
;     ...
;     float* So = F.out + O_SH + ((size_t)(b * 4 + h) * 128 + kq * 32) * 128 + v;
; #pragma unroll
;     for (int j = 0; j < 32; ++j) So[(size_t)j * 128] = S[j];
;     if (F.wave < 4) {
;         const int t = F.wave, lane = F.lane; const f32x2 o = *(const LAS f32x2*)(Lot + t * 128 + 2 * lane);
;         const float ss = wave_sum(o.x * o.x + o.y * o.y); const float rr = 1.0f / sqrtf(ss * (1.f / 128.f) + EPS);
;         const size_t go = (size_t)(T + b * 4 + t) * 512 + h * 128 + 2 * lane; const unsigned gw_ = *(const unsigned*)(wsp<bf16>(F, WS_HG) + go);
;         *(unsigned*)(wsp<bf16>(F, WS_OB) + go) = pk2(o.x * rr * ((const float*)F.A.in[20])[2 * lane] * bflo(gw_), o.y * rr * ((const float*)F.A.in[20])[2 * lane + 1] * bfhi(gw_)); }
.LBB0_1681:
	s_or_b64 exec, exec, s[22:23]
	v_lshl_add_u64 v[18:19], v[18:19], 2, v[12:13]
	v_add_co_u32_e32 v28, vcc, 0x1000, v18
	s_waitcnt lgkmcnt(0)
	s_nop 0
	v_addc_co_u32_e32 v29, vcc, 0, v19, vcc
	s_barrier
	global_store_dword v[18:19], v69, off
	global_store_dword v[18:19], v70, off offset:512
	global_store_dword v[18:19], v71, off offset:1024
	global_store_dword v[18:19], v72, off offset:1536
	global_store_dword v[18:19], v73, off offset:2048
	global_store_dword v[18:19], v74, off offset:2560
	global_store_dword v[18:19], v75, off offset:3072
	global_store_dword v[18:19], v76, off offset:3584
	global_store_dword v[28:29], v61, off
	global_store_dword v[28:29], v62, off offset:512
	global_store_dword v[28:29], v63, off offset:1024
	global_store_dword v[28:29], v64, off offset:1536
	global_store_dword v[28:29], v65, off offset:2048
	global_store_dword v[28:29], v66, off offset:2560
	global_store_dword v[28:29], v67, off offset:3072
	global_store_dword v[28:29], v68, off offset:3584
	v_add_co_u32_e32 v28, vcc, 0x2000, v18
	s_nop 1
	v_addc_co_u32_e32 v29, vcc, 0, v19, vcc
	v_add_co_u32_e32 v18, vcc, s30, v18
	global_store_dword v[28:29], v57, off
	global_store_dword v[28:29], v58, off offset:512
	global_store_dword v[28:29], v59, off offset:1024
	global_store_dword v[28:29], v60, off offset:1536
	global_store_dword v[28:29], v36, off offset:2048
	global_store_dword v[28:29], v37, off offset:2560
	global_store_dword v[28:29], v34, off offset:3072
	global_store_dword v[28:29], v35, off offset:3584
	v_addc_co_u32_e32 v19, vcc, 0, v19, vcc
	s_andn2_b64 vcc, exec, s[20:21]
	global_store_dword v[18:19], v26, off
	global_store_dword v[18:19], v27, off offset:512
	global_store_dword v[18:19], v24, off offset:1024
	global_store_dword v[18:19], v25, off offset:1536
	global_store_dword v[18:19], v20, off offset:2048
	global_store_dword v[18:19], v21, off offset:2560
	global_store_dword v[18:19], v22, off offset:3072
	global_store_dword v[18:19], v23, off offset:3584
	s_cbranch_vccnz .LBB0_1666
	ds_read_b64 v[18:19], v15 offset:8192
	v_and_b32_e32 v20, 64, v139
	v_xor_b32_e32 v22, 1, v139
	v_add_u32_e32 v26, 64, v20
	v_cmp_lt_i32_e32 vcc, v22, v26
	s_waitcnt lgkmcnt(0)
	v_pk_mul_f32 v[20:21], v[18:19], v[18:19]
	s_add_i32 s4, s4, s79
	v_add_f32_e32 v20, v20, v21
	v_cndmask_b32_e32 v21, v139, v22, vcc
	v_lshlrev_b32_e32 v21, 2, v21
	ds_bpermute_b32 v21, v21, v20
	v_xor_b32_e32 v22, 2, v139
	v_cmp_lt_i32_e32 vcc, v22, v26
	s_ashr_i32 s5, s4, 31
	s_lshl_b64 s[4:5], s[4:5], 9
	s_waitcnt lgkmcnt(0)
	v_add_f32_e32 v27, v20, v21
	v_cndmask_b32_e32 v20, v139, v22, vcc
	v_lshlrev_b32_e32 v20, 2, v20
	ds_bpermute_b32 v28, v20, v27
	v_mov_b32_e32 v20, s24
	v_or3_b32 v21, s5, 0, 0
	v_or3_b32 v20, s4, v20, v14
	v_lshlrev_b64 v[20:21], 1, v[20:21]
	s_waitcnt lgkmcnt(0)
	v_add_f32_e32 v22, v27, v28
	v_xor_b32_e32 v27, 4, v139
	v_cmp_lt_i32_e32 vcc, v27, v26
	s_nop 1
	v_cndmask_b32_e32 v27, v139, v27, vcc
	v_lshlrev_b32_e32 v27, 2, v27
	ds_bpermute_b32 v27, v27, v22
	s_waitcnt lgkmcnt(0)
	v_add_f32_e32 v22, v22, v27
	v_xor_b32_e32 v27, 8, v139
	v_cmp_lt_i32_e32 vcc, v27, v26
	s_nop 1
	v_cndmask_b32_e32 v27, v139, v27, vcc
	v_lshlrev_b32_e32 v27, 2, v27
	ds_bpermute_b32 v27, v27, v22
	s_waitcnt lgkmcnt(0)
	v_add_f32_e32 v22, v22, v27
	v_xor_b32_e32 v27, 16, v139
	v_cmp_lt_i32_e32 vcc, v27, v26
	s_nop 1
	v_cndmask_b32_e32 v27, v139, v27, vcc
	v_lshlrev_b32_e32 v27, 2, v27
	ds_bpermute_b32 v27, v27, v22
	s_waitcnt lgkmcnt(0)
	v_add_f32_e32 v22, v22, v27
	v_xor_b32_e32 v27, 32, v139
	v_cmp_lt_i32_e32 vcc, v27, v26
	s_nop 1
	v_cndmask_b32_e32 v26, v139, v27, vcc
	v_lshlrev_b32_e32 v26, 2, v26
	ds_bpermute_b32 v26, v26, v22
	s_waitcnt lgkmcnt(0)
	v_add_f32_e32 v22, v22, v26
	v_fmamk_f32 v22, v22, 0x3c000000, v38
	v_mul_f32_e32 v26, 0x4f800000, v22
	v_cmp_gt_f32_e32 vcc, s31, v22
	s_nop 1
	v_cndmask_b32_e32 v22, v22, v26, vcc
	v_sqrt_f32_e32 v26, v22
	s_nop 0
	v_add_u32_e32 v27, -1, v26
	v_add_u32_e32 v28, 1, v26
	v_fma_f32 v29, -v27, v26, v22
	v_fma_f32 v30, -v28, v26, v22
	v_cmp_ge_f32_e64 s[4:5], 0, v29
	s_nop 1
	v_cndmask_b32_e64 v26, v26, v27, s[4:5]
	v_cmp_lt_f32_e64 s[4:5], 0, v30
	s_nop 1
	v_cndmask_b32_e64 v26, v26, v28, s[4:5]
	v_mul_f32_e32 v27, 0x37800000, v26
	v_cndmask_b32_e32 v26, v26, v27, vcc
	v_cmp_class_f32_e32 vcc, v22, v39
	s_nop 1
	v_cndmask_b32_e32 v22, v26, v22, vcc
	v_div_scale_f32 v26, s[4:5], v22, v22, 1.0
	v_rcp_f32_e32 v27, v26
	v_div_scale_f32 v28, vcc, 1.0, v22, 1.0
	v_fma_f32 v29, -v26, v27, 1.0
	v_fmac_f32_e32 v27, v29, v27
	v_mul_f32_e32 v29, v28, v27
	v_fma_f32 v30, -v26, v29, v28
	v_fmac_f32_e32 v29, v30, v27
	v_fma_f32 v26, -v26, v29, v28
	v_div_fmas_f32 v26, v26, v27, v29
	v_div_fixup_f32 v22, v26, v22, 1.0
	s_waitcnt vmcnt(32)
	v_pk_mul_f32 v[18:19], v[18:19], v[22:23] op_sel_hi:[1,0]
	v_lshlrev_b32_e32 v22, 16, v234
	v_pk_mul_f32 v[18:19], v[232:233], v[18:19]
	v_and_b32_e32 v23, 0xffff0000, v234
	v_pk_mul_f32 v[18:19], v[18:19], v[22:23]
	s_nop 0
	v_cvt_pk_bf16_f32 v22, v18, v19
	v_lshl_add_u64 v[18:19], s[8:9], 0, v[20:21]
	global_store_dword v[18:19], v22, off
	s_branch .LBB0_1666
